# P4 EpiRes epilogue: hoist 16 residual loads to top of epilogue, single wait
# speedup vs baseline: 1.0059x; 1.0059x over previous
; #define LAS __attribute__((address_space(3)))
; DI float shx(float v, int m, int lane) { return __builtin_bit_cast(float, __builtin_amdgcn_ds_bpermute((lane ^ m) << 2, __builtin_bit_cast(int, v))); }
; DI unsigned pk2(float lo, float hi) { f32x2_t v = {lo, hi}; bf16x2_t b = __builtin_convertvector(v, bf16x2_t); return __builtin_bit_cast(unsigned, b); }
;     DI void operator()(const f32x4 (&acc)[2][2][4][2], const pg8::Unit& u, int wr, int wc, int fr, int fq) const {
;     ...
;         for (int ai = 0; ai < 2; ++ai)
; #pragma unroll
;             for (int m = 0; m < 4; ++m) {
;                 const int row = u.pm * 256 + ai * 128 + wr * 64 + m * 16 + fr;
;                 float sq = 0.f;
; #pragma unroll
;                 for (int bj = 0; bj < 2; ++bj) {
;                     const size_t off = (size_t)row * DM + u.pn * 256 + bj * 128 + wc * 32 + 8 * fq;
;                     const u32x4 r = *(const u32x4*)(xb + off);
;                     f32x4 a, b;
;                     a[0] = __builtin_bit_cast(float, r.x << 16); a[1] = __builtin_bit_cast(float, r.x & 0xffff0000u); a[2] = __builtin_bit_cast(float, r.y << 16); a[3] = __builtin_bit_cast(float, r.y & 0xffff0000u);
;                     b[0] = __builtin_bit_cast(float, r.z << 16); b[1] = __builtin_bit_cast(float, r.z & 0xffff0000u); b[2] = __builtin_bit_cast(float, r.w << 16); b[3] = __builtin_bit_cast(float, r.w & 0xffff0000u);
;                     a += acc[ai][bj][m][0]; b += acc[ai][bj][m][1];
;                     if (xout) { *(f32x4*)(xout + off) = a; *(f32x4*)(xout + off + 4) = b; }
;                     else { u32x4 w; w.x = pk2(a[0], a[1]); w.y = pk2(a[2], a[3]); w.z = pk2(b[0], b[1]); w.w = pk2(b[2], b[3]); *(u32x4*)(xb + off) = w; }
;                     sq += (a[0] * a[0] + a[1] * a[1]) + (a[2] * a[2] + a[3] * a[3]) + (b[0] * b[0] + b[1] * b[1]) + (b[2] * b[2] + b[3] * b[3]);
;                 }
;                 if (ssout) { const int lane_ = fq * 16 + fr; sq += shx(sq, 16, lane_); sq += shx(sq, 32, lane_);
;                     if (fq == 0) *(LAS float*)(red + ((ai * 128 + wr * 64 + m * 16 + fr) * 4 + wc) * 4) = sq; }
.LBB0_1155:
	s_lshl_b32 s18, s18, 8
	v_add_u32_e32 v146, s18, v139
	v_ashrrev_i32_e32 v147, 31, v146
	v_readlane_b32 s28, v254, 54
	s_lshl_b32 s20, s20, 8
	v_lshlrev_b64 v[162:163], 12, v[146:147]
	v_readlane_b32 s29, v254, 55
	s_ashr_i32 s21, s20, 31
	v_lshlrev_b32_e32 v0, 1, v138
	v_lshl_add_u64 v[162:163], s[28:29], 0, v[162:163]
	v_lshl_add_u64 v[162:163], s[20:21], 1, v[162:163]
	v_lshl_add_u64 v[166:167], v[162:163], 0, v[0:1]
	s_mov_b32 s23, 0
	global_load_dwordx4 v[172:175], v[166:167], off
	global_load_dwordx4 v[176:179], v[166:167], off offset:256
	s_mov_b32 s22, 0x10000
	v_lshl_add_u64 v[164:165], s[22:23], 0, v[166:167]
	global_load_dwordx4 v[180:183], v[164:165], off
	global_load_dwordx4 v[184:187], v[164:165], off offset:256
	s_mov_b32 s22, 0x20000
	v_lshl_add_u64 v[164:165], s[22:23], 0, v[166:167]
	global_load_dwordx4 v[196:199], v[164:165], off
	global_load_dwordx4 v[200:203], v[164:165], off offset:256
	s_mov_b32 s22, 0x30000
	v_lshl_add_u64 v[164:165], s[22:23], 0, v[166:167]
	global_load_dwordx4 v[204:207], v[164:165], off
	global_load_dwordx4 v[208:211], v[164:165], off offset:256
	s_mov_b32 s22, 0x80000
	v_lshl_add_u64 v[164:165], s[22:23], 0, v[166:167]
	global_load_dwordx4 v[212:215], v[164:165], off
	global_load_dwordx4 v[216:219], v[164:165], off offset:256
	s_mov_b32 s22, 0x90000
	v_lshl_add_u64 v[164:165], s[22:23], 0, v[166:167]
	global_load_dwordx4 v[220:223], v[164:165], off
	global_load_dwordx4 v[224:227], v[164:165], off offset:256
	s_mov_b32 s22, 0xa0000
	v_lshl_add_u64 v[164:165], s[22:23], 0, v[166:167]
	global_load_dwordx4 v[236:239], v[164:165], off
	global_load_dwordx4 v[240:243], v[164:165], off offset:256
	s_mov_b32 s22, 0xb0000
	v_lshl_add_u64 v[164:165], s[22:23], 0, v[166:167]
	global_load_dwordx4 v[244:247], v[164:165], off
	global_load_dwordx4 v[248:251], v[164:165], off offset:256
	s_waitcnt vmcnt(0)
	v_lshlrev_b32_e32 v168, 16, v172
	v_and_b32_e32 v169, 0xffff0000, v172
	v_lshlrev_b32_e32 v162, 16, v173
	v_and_b32_e32 v163, 0xffff0000, v173
	v_lshlrev_b32_e32 v170, 16, v174
	v_and_b32_e32 v171, 0xffff0000, v174
	v_lshlrev_b32_e32 v164, 16, v175
	v_and_b32_e32 v165, 0xffff0000, v175
	v_pk_add_f32 v[128:129], v[128:129], v[162:163]
	v_pk_add_f32 v[126:127], v[126:127], v[168:169]
	v_pk_add_f32 v[162:163], v[124:125], v[164:165]
	v_pk_add_f32 v[164:165], v[122:123], v[170:171]
	v_cvt_pk_bf16_f32 v122, v126, v127
	v_cvt_pk_bf16_f32 v123, v128, v129
	v_cvt_pk_bf16_f32 v124, v164, v165
	v_cvt_pk_bf16_f32 v125, v162, v163
	flat_store_dwordx4 v[166:167], v[122:125]
	s_nop 1
	v_mul_f32_e32 v122, v127, v127
	v_mul_f32_e32 v123, v129, v129
	v_fmac_f32_e32 v122, v126, v126
	v_fmac_f32_e32 v123, v128, v128
	v_add_f32_e32 v122, v122, v123
	v_mul_f32_e32 v123, v165, v165
	v_fmac_f32_e32 v123, v164, v164
	v_add_f32_e32 v122, v123, v122
	v_mul_f32_e32 v123, v163, v163
	v_fmac_f32_e32 v123, v162, v162
	v_add_f32_e32 v147, v123, v122
	v_lshlrev_b32_e32 v126, 16, v176
	v_and_b32_e32 v127, 0xffff0000, v176
	v_lshlrev_b32_e32 v122, 16, v177
	v_and_b32_e32 v123, 0xffff0000, v177
	v_lshlrev_b32_e32 v128, 16, v178
	v_and_b32_e32 v129, 0xffff0000, v178
	v_lshlrev_b32_e32 v124, 16, v179
	v_and_b32_e32 v125, 0xffff0000, v179
	v_pk_add_f32 v[120:121], v[120:121], v[122:123]
	v_pk_add_f32 v[118:119], v[118:119], v[126:127]
	v_pk_add_f32 v[122:123], v[116:117], v[124:125]
	v_pk_add_f32 v[124:125], v[114:115], v[128:129]
	v_cvt_pk_bf16_f32 v114, v118, v119
	v_cvt_pk_bf16_f32 v115, v120, v121
	v_cvt_pk_bf16_f32 v116, v124, v125
	v_cvt_pk_bf16_f32 v117, v122, v123
	flat_store_dwordx4 v[166:167], v[114:117] offset:256
	s_nop 1
	v_mul_f32_e32 v116, v119, v119
	v_mul_f32_e32 v117, v121, v121
	v_mul_f32_e32 v115, v125, v125
	v_fmac_f32_e32 v116, v118, v118
	v_fmac_f32_e32 v117, v120, v120
	v_mul_f32_e32 v114, v123, v123
	v_fmac_f32_e32 v115, v124, v124
	v_add_f32_e32 v116, v116, v117
	v_fmac_f32_e32 v114, v122, v122
	v_add_f32_e32 v115, v115, v116
	v_add_f32_e32 v114, v114, v115
	v_add_f32_e32 v114, v147, v114
	ds_bpermute_b32 v115, v149, v114
	s_waitcnt lgkmcnt(0)
	v_add_f32_e32 v114, v114, v115
	ds_bpermute_b32 v115, v150, v114
	s_and_saveexec_b64 s[22:23], s[40:41]
	v_readlane_b32 s54, v254, 62
	s_movk_i32 s53, 0x5880
	v_readlane_b32 s55, v254, 63
	s_cbranch_execz .LBB0_1157
	s_waitcnt lgkmcnt(0)
	v_add_f32_e32 v114, v114, v115
	ds_write_b32 v161, v114
; #define LAS __attribute__((address_space(3)))
; DI float shx(float v, int m, int lane) { return __builtin_bit_cast(float, __builtin_amdgcn_ds_bpermute((lane ^ m) << 2, __builtin_bit_cast(int, v))); }
; DI unsigned pk2(float lo, float hi) { f32x2_t v = {lo, hi}; bf16x2_t b = __builtin_convertvector(v, bf16x2_t); return __builtin_bit_cast(unsigned, b); }
;     DI void operator()(const f32x4 (&acc)[2][2][4][2], const pg8::Unit& u, int wr, int wc, int fr, int fq) const {
;     ...
;             for (int m = 0; m < 4; ++m) {
;                 const int row = u.pm * 256 + ai * 128 + wr * 64 + m * 16 + fr;
;                 float sq = 0.f;
; #pragma unroll
;                 for (int bj = 0; bj < 2; ++bj) {
;                     const size_t off = (size_t)row * DM + u.pn * 256 + bj * 128 + wc * 32 + 8 * fq;
;                     const u32x4 r = *(const u32x4*)(xb + off);
;                     f32x4 a, b;
;                     a[0] = __builtin_bit_cast(float, r.x << 16); a[1] = __builtin_bit_cast(float, r.x & 0xffff0000u); a[2] = __builtin_bit_cast(float, r.y << 16); a[3] = __builtin_bit_cast(float, r.y & 0xffff0000u);
;                     b[0] = __builtin_bit_cast(float, r.z << 16); b[1] = __builtin_bit_cast(float, r.z & 0xffff0000u); b[2] = __builtin_bit_cast(float, r.w << 16); b[3] = __builtin_bit_cast(float, r.w & 0xffff0000u);
;                     a += acc[ai][bj][m][0]; b += acc[ai][bj][m][1];
;                     if (xout) { *(f32x4*)(xout + off) = a; *(f32x4*)(xout + off + 4) = b; }
;                     else { u32x4 w; w.x = pk2(a[0], a[1]); w.y = pk2(a[2], a[3]); w.z = pk2(b[0], b[1]); w.w = pk2(b[2], b[3]); *(u32x4*)(xb + off) = w; }
;                     sq += (a[0] * a[0] + a[1] * a[1]) + (a[2] * a[2] + a[3] * a[3]) + (b[0] * b[0] + b[1] * b[1]) + (b[2] * b[2] + b[3] * b[3]);
;                 }
;                 if (ssout) { const int lane_ = fq * 16 + fr; sq += shx(sq, 16, lane_); sq += shx(sq, 32, lane_);
;                     if (fq == 0) *(LAS float*)(red + ((ai * 128 + wr * 64 + m * 16 + fr) * 4 + wc) * 4) = sq; }
.LBB0_1157:
	s_or_b64 exec, exec, s[22:23]
	v_add_u32_e32 v114, s18, v151
	s_waitcnt lgkmcnt(0)
	v_ashrrev_i32_e32 v115, 31, v114
	v_lshlrev_b64 v[114:115], 12, v[114:115]
	v_lshl_add_u64 v[114:115], s[28:29], 0, v[114:115]
	v_lshl_add_u64 v[114:115], s[20:21], 1, v[114:115]
	v_lshl_add_u64 v[118:119], v[114:115], 0, v[0:1]
	v_lshlrev_b32_e32 v120, 16, v180
	v_and_b32_e32 v121, 0xffff0000, v180
	v_lshlrev_b32_e32 v114, 16, v181
	v_and_b32_e32 v115, 0xffff0000, v181
	v_lshlrev_b32_e32 v122, 16, v182
	v_and_b32_e32 v123, 0xffff0000, v182
	v_lshlrev_b32_e32 v116, 16, v183
	v_and_b32_e32 v117, 0xffff0000, v183
	v_pk_add_f32 v[112:113], v[112:113], v[114:115]
	v_pk_add_f32 v[110:111], v[110:111], v[120:121]
	v_pk_add_f32 v[114:115], v[108:109], v[116:117]
	v_pk_add_f32 v[116:117], v[106:107], v[122:123]
	v_cvt_pk_bf16_f32 v106, v110, v111
	v_cvt_pk_bf16_f32 v107, v112, v113
	v_cvt_pk_bf16_f32 v108, v116, v117
	v_cvt_pk_bf16_f32 v109, v114, v115
	flat_store_dwordx4 v[118:119], v[106:109]
	s_nop 1
	v_mul_f32_e32 v106, v111, v111
	v_mul_f32_e32 v107, v113, v113
	v_fmac_f32_e32 v106, v110, v110
	v_fmac_f32_e32 v107, v112, v112
	v_add_f32_e32 v106, v106, v107
	v_mul_f32_e32 v107, v117, v117
	v_fmac_f32_e32 v107, v116, v116
	v_add_f32_e32 v106, v107, v106
	v_mul_f32_e32 v107, v115, v115
	v_fmac_f32_e32 v107, v114, v114
	v_add_f32_e32 v114, v107, v106
	v_lshlrev_b32_e32 v110, 16, v184
	v_and_b32_e32 v111, 0xffff0000, v184
	v_lshlrev_b32_e32 v106, 16, v185
	v_and_b32_e32 v107, 0xffff0000, v185
	v_lshlrev_b32_e32 v112, 16, v186
	v_and_b32_e32 v113, 0xffff0000, v186
	v_lshlrev_b32_e32 v108, 16, v187
	v_and_b32_e32 v109, 0xffff0000, v187
	v_pk_add_f32 v[104:105], v[104:105], v[106:107]
	v_pk_add_f32 v[102:103], v[102:103], v[110:111]
	v_pk_add_f32 v[106:107], v[100:101], v[108:109]
	v_pk_add_f32 v[108:109], v[98:99], v[112:113]
	v_cvt_pk_bf16_f32 v98, v102, v103
	v_cvt_pk_bf16_f32 v99, v104, v105
	v_cvt_pk_bf16_f32 v100, v108, v109
	v_cvt_pk_bf16_f32 v101, v106, v107
	flat_store_dwordx4 v[118:119], v[98:101] offset:256
	s_nop 1
	v_mul_f32_e32 v100, v103, v103
	v_mul_f32_e32 v101, v105, v105
	v_mul_f32_e32 v99, v109, v109
	v_fmac_f32_e32 v100, v102, v102
	v_fmac_f32_e32 v101, v104, v104
	v_mul_f32_e32 v98, v107, v107
	v_fmac_f32_e32 v99, v108, v108
	v_add_f32_e32 v100, v100, v101
	v_fmac_f32_e32 v98, v106, v106
	v_add_f32_e32 v99, v99, v100
	v_add_f32_e32 v98, v98, v99
	v_add_f32_e32 v98, v114, v98
	ds_bpermute_b32 v99, v149, v98
	s_waitcnt lgkmcnt(0)
	v_add_f32_e32 v98, v98, v99
	ds_bpermute_b32 v99, v150, v98
	s_and_saveexec_b64 s[22:23], s[40:41]
	s_cbranch_execz .LBB0_1159
	s_waitcnt lgkmcnt(0)
	v_add_f32_e32 v98, v98, v99
	ds_write_b32 v156, v98
.LBB0_1159:
	s_or_b64 exec, exec, s[22:23]
	v_add_u32_e32 v98, s18, v152
	s_waitcnt lgkmcnt(0)
	v_ashrrev_i32_e32 v99, 31, v98
	v_lshlrev_b64 v[98:99], 12, v[98:99]
	v_lshl_add_u64 v[98:99], s[28:29], 0, v[98:99]
	v_lshl_add_u64 v[98:99], s[20:21], 1, v[98:99]
	v_lshl_add_u64 v[102:103], v[98:99], 0, v[0:1]
	v_lshlrev_b32_e32 v104, 16, v196
	v_and_b32_e32 v105, 0xffff0000, v196
	v_lshlrev_b32_e32 v98, 16, v197
	v_and_b32_e32 v99, 0xffff0000, v197
	v_lshlrev_b32_e32 v106, 16, v198
	v_and_b32_e32 v107, 0xffff0000, v198
	v_lshlrev_b32_e32 v100, 16, v199
	v_and_b32_e32 v101, 0xffff0000, v199
	v_pk_add_f32 v[96:97], v[96:97], v[98:99]
	v_pk_add_f32 v[94:95], v[94:95], v[104:105]
	v_pk_add_f32 v[98:99], v[92:93], v[100:101]
	v_pk_add_f32 v[100:101], v[90:91], v[106:107]
	v_cvt_pk_bf16_f32 v90, v94, v95
	v_cvt_pk_bf16_f32 v91, v96, v97
	v_cvt_pk_bf16_f32 v92, v100, v101
	v_cvt_pk_bf16_f32 v93, v98, v99
	flat_store_dwordx4 v[102:103], v[90:93]
	s_nop 1
	v_mul_f32_e32 v90, v95, v95
	v_mul_f32_e32 v91, v97, v97
	v_fmac_f32_e32 v90, v94, v94
	v_fmac_f32_e32 v91, v96, v96
	v_add_f32_e32 v90, v90, v91
	v_mul_f32_e32 v91, v101, v101
	v_fmac_f32_e32 v91, v100, v100
	v_add_f32_e32 v90, v91, v90
	v_mul_f32_e32 v91, v99, v99
	v_fmac_f32_e32 v91, v98, v98
	v_add_f32_e32 v98, v91, v90
	v_lshlrev_b32_e32 v94, 16, v200
	v_and_b32_e32 v95, 0xffff0000, v200
	v_lshlrev_b32_e32 v90, 16, v201
	v_and_b32_e32 v91, 0xffff0000, v201
	v_lshlrev_b32_e32 v96, 16, v202
	v_and_b32_e32 v97, 0xffff0000, v202
	v_lshlrev_b32_e32 v92, 16, v203
	v_and_b32_e32 v93, 0xffff0000, v203
	v_pk_add_f32 v[88:89], v[88:89], v[90:91]
	v_pk_add_f32 v[86:87], v[86:87], v[94:95]
	v_pk_add_f32 v[90:91], v[84:85], v[92:93]
	v_pk_add_f32 v[92:93], v[82:83], v[96:97]
	v_cvt_pk_bf16_f32 v82, v86, v87
	v_cvt_pk_bf16_f32 v83, v88, v89
	v_cvt_pk_bf16_f32 v84, v92, v93
	v_cvt_pk_bf16_f32 v85, v90, v91
	flat_store_dwordx4 v[102:103], v[82:85] offset:256
	s_nop 1
	v_mul_f32_e32 v84, v87, v87
	v_mul_f32_e32 v85, v89, v89
	v_mul_f32_e32 v83, v93, v93
	v_fmac_f32_e32 v84, v86, v86
	v_fmac_f32_e32 v85, v88, v88
	v_mul_f32_e32 v82, v91, v91
	v_fmac_f32_e32 v83, v92, v92
	v_add_f32_e32 v84, v84, v85
	v_fmac_f32_e32 v82, v90, v90
	v_add_f32_e32 v83, v83, v84
	v_add_f32_e32 v82, v82, v83
	v_add_f32_e32 v82, v98, v82
	ds_bpermute_b32 v83, v149, v82
	s_waitcnt lgkmcnt(0)
	v_add_f32_e32 v82, v82, v83
	ds_bpermute_b32 v83, v150, v82
	s_and_saveexec_b64 s[22:23], s[40:41]
	s_cbranch_execz .LBB0_1161
	s_waitcnt lgkmcnt(0)
	v_add_f32_e32 v82, v82, v83
	ds_write_b32 v157, v82
; #define LAS __attribute__((address_space(3)))
; DI float shx(float v, int m, int lane) { return __builtin_bit_cast(float, __builtin_amdgcn_ds_bpermute((lane ^ m) << 2, __builtin_bit_cast(int, v))); }
; DI unsigned pk2(float lo, float hi) { f32x2_t v = {lo, hi}; bf16x2_t b = __builtin_convertvector(v, bf16x2_t); return __builtin_bit_cast(unsigned, b); }
;     DI void operator()(const f32x4 (&acc)[2][2][4][2], const pg8::Unit& u, int wr, int wc, int fr, int fq) const {
;     ...
;             for (int m = 0; m < 4; ++m) {
;                 const int row = u.pm * 256 + ai * 128 + wr * 64 + m * 16 + fr;
;                 float sq = 0.f;
; #pragma unroll
;                 for (int bj = 0; bj < 2; ++bj) {
;                     const size_t off = (size_t)row * DM + u.pn * 256 + bj * 128 + wc * 32 + 8 * fq;
;                     const u32x4 r = *(const u32x4*)(xb + off);
;                     f32x4 a, b;
;                     a[0] = __builtin_bit_cast(float, r.x << 16); a[1] = __builtin_bit_cast(float, r.x & 0xffff0000u); a[2] = __builtin_bit_cast(float, r.y << 16); a[3] = __builtin_bit_cast(float, r.y & 0xffff0000u);
;                     b[0] = __builtin_bit_cast(float, r.z << 16); b[1] = __builtin_bit_cast(float, r.z & 0xffff0000u); b[2] = __builtin_bit_cast(float, r.w << 16); b[3] = __builtin_bit_cast(float, r.w & 0xffff0000u);
;                     a += acc[ai][bj][m][0]; b += acc[ai][bj][m][1];
;                     if (xout) { *(f32x4*)(xout + off) = a; *(f32x4*)(xout + off + 4) = b; }
;                     else { u32x4 w; w.x = pk2(a[0], a[1]); w.y = pk2(a[2], a[3]); w.z = pk2(b[0], b[1]); w.w = pk2(b[2], b[3]); *(u32x4*)(xb + off) = w; }
;                     sq += (a[0] * a[0] + a[1] * a[1]) + (a[2] * a[2] + a[3] * a[3]) + (b[0] * b[0] + b[1] * b[1]) + (b[2] * b[2] + b[3] * b[3]);
;                 }
;                 if (ssout) { const int lane_ = fq * 16 + fr; sq += shx(sq, 16, lane_); sq += shx(sq, 32, lane_);
;                     if (fq == 0) *(LAS float*)(red + ((ai * 128 + wr * 64 + m * 16 + fr) * 4 + wc) * 4) = sq; }
.LBB0_1161:
	s_or_b64 exec, exec, s[22:23]
	v_add_u32_e32 v82, s18, v153
	s_waitcnt lgkmcnt(0)
	v_ashrrev_i32_e32 v83, 31, v82
	v_lshlrev_b64 v[82:83], 12, v[82:83]
	v_lshl_add_u64 v[82:83], s[28:29], 0, v[82:83]
	v_lshl_add_u64 v[82:83], s[20:21], 1, v[82:83]
	v_lshl_add_u64 v[86:87], v[82:83], 0, v[0:1]
	v_lshlrev_b32_e32 v88, 16, v204
	v_and_b32_e32 v89, 0xffff0000, v204
	v_lshlrev_b32_e32 v82, 16, v205
	v_and_b32_e32 v83, 0xffff0000, v205
	v_lshlrev_b32_e32 v90, 16, v206
	v_and_b32_e32 v91, 0xffff0000, v206
	v_lshlrev_b32_e32 v84, 16, v207
	v_and_b32_e32 v85, 0xffff0000, v207
	v_pk_add_f32 v[80:81], v[80:81], v[82:83]
	v_pk_add_f32 v[78:79], v[78:79], v[88:89]
	v_pk_add_f32 v[82:83], v[76:77], v[84:85]
	v_pk_add_f32 v[84:85], v[74:75], v[90:91]
	v_cvt_pk_bf16_f32 v74, v78, v79
	v_cvt_pk_bf16_f32 v75, v80, v81
	v_cvt_pk_bf16_f32 v76, v84, v85
	v_cvt_pk_bf16_f32 v77, v82, v83
	flat_store_dwordx4 v[86:87], v[74:77]
	s_nop 1
	v_mul_f32_e32 v74, v79, v79
	v_mul_f32_e32 v75, v81, v81
	v_fmac_f32_e32 v74, v78, v78
	v_fmac_f32_e32 v75, v80, v80
	v_add_f32_e32 v74, v74, v75
	v_mul_f32_e32 v75, v85, v85
	v_fmac_f32_e32 v75, v84, v84
	v_add_f32_e32 v74, v75, v74
	v_mul_f32_e32 v75, v83, v83
	v_fmac_f32_e32 v75, v82, v82
	v_add_f32_e32 v82, v75, v74
	v_lshlrev_b32_e32 v78, 16, v208
	v_and_b32_e32 v79, 0xffff0000, v208
	v_lshlrev_b32_e32 v74, 16, v209
	v_and_b32_e32 v75, 0xffff0000, v209
	v_lshlrev_b32_e32 v80, 16, v210
	v_and_b32_e32 v81, 0xffff0000, v210
	v_lshlrev_b32_e32 v76, 16, v211
	v_and_b32_e32 v77, 0xffff0000, v211
	v_pk_add_f32 v[72:73], v[72:73], v[74:75]
	v_pk_add_f32 v[70:71], v[70:71], v[78:79]
	v_pk_add_f32 v[74:75], v[68:69], v[76:77]
	v_pk_add_f32 v[76:77], v[66:67], v[80:81]
	v_cvt_pk_bf16_f32 v66, v70, v71
	v_cvt_pk_bf16_f32 v67, v72, v73
	v_cvt_pk_bf16_f32 v68, v76, v77
	v_cvt_pk_bf16_f32 v69, v74, v75
	flat_store_dwordx4 v[86:87], v[66:69] offset:256
	s_nop 1
	v_mul_f32_e32 v68, v71, v71
	v_mul_f32_e32 v69, v73, v73
	v_mul_f32_e32 v67, v77, v77
	v_fmac_f32_e32 v68, v70, v70
	v_fmac_f32_e32 v69, v72, v72
	v_mul_f32_e32 v66, v75, v75
	v_fmac_f32_e32 v67, v76, v76
	v_add_f32_e32 v68, v68, v69
	v_fmac_f32_e32 v66, v74, v74
	v_add_f32_e32 v67, v67, v68
	v_add_f32_e32 v66, v66, v67
	v_add_f32_e32 v66, v82, v66
	ds_bpermute_b32 v67, v149, v66
	s_waitcnt lgkmcnt(0)
	v_add_f32_e32 v66, v66, v67
	ds_bpermute_b32 v67, v150, v66
	s_and_saveexec_b64 s[22:23], s[40:41]
	s_cbranch_execz .LBB0_1163
	s_waitcnt lgkmcnt(0)
	v_add_f32_e32 v66, v66, v67
	ds_write_b32 v158, v66
.LBB0_1163:
	s_or_b64 exec, exec, s[22:23]
	v_add_u32_e32 v66, s18, v154
	s_waitcnt lgkmcnt(0)
	v_ashrrev_i32_e32 v67, 31, v66
	v_lshlrev_b64 v[66:67], 12, v[66:67]
	v_lshl_add_u64 v[66:67], s[28:29], 0, v[66:67]
	v_lshl_add_u64 v[66:67], s[20:21], 1, v[66:67]
	v_lshl_add_u64 v[70:71], v[66:67], 0, v[0:1]
	v_lshlrev_b32_e32 v72, 16, v212
	v_and_b32_e32 v73, 0xffff0000, v212
	v_lshlrev_b32_e32 v66, 16, v213
	v_and_b32_e32 v67, 0xffff0000, v213
	v_lshlrev_b32_e32 v74, 16, v214
	v_and_b32_e32 v75, 0xffff0000, v214
	v_lshlrev_b32_e32 v68, 16, v215
	v_and_b32_e32 v69, 0xffff0000, v215
	v_pk_add_f32 v[64:65], v[64:65], v[66:67]
	v_pk_add_f32 v[62:63], v[62:63], v[72:73]
	v_pk_add_f32 v[66:67], v[60:61], v[68:69]
	v_pk_add_f32 v[68:69], v[58:59], v[74:75]
	v_cvt_pk_bf16_f32 v58, v62, v63
	v_cvt_pk_bf16_f32 v59, v64, v65
	v_cvt_pk_bf16_f32 v60, v68, v69
	v_cvt_pk_bf16_f32 v61, v66, v67
	flat_store_dwordx4 v[70:71], v[58:61]
	s_nop 1
	v_mul_f32_e32 v58, v63, v63
	v_mul_f32_e32 v59, v65, v65
	v_fmac_f32_e32 v58, v62, v62
	v_fmac_f32_e32 v59, v64, v64
	v_add_f32_e32 v58, v58, v59
	v_mul_f32_e32 v59, v69, v69
	v_fmac_f32_e32 v59, v68, v68
	v_add_f32_e32 v58, v59, v58
	v_mul_f32_e32 v59, v67, v67
	v_fmac_f32_e32 v59, v66, v66
	v_add_f32_e32 v66, v59, v58
	v_lshlrev_b32_e32 v62, 16, v216
	v_and_b32_e32 v63, 0xffff0000, v216
	v_lshlrev_b32_e32 v58, 16, v217
	v_and_b32_e32 v59, 0xffff0000, v217
	v_lshlrev_b32_e32 v64, 16, v218
	v_and_b32_e32 v65, 0xffff0000, v218
	v_lshlrev_b32_e32 v60, 16, v219
	v_and_b32_e32 v61, 0xffff0000, v219
	v_pk_add_f32 v[56:57], v[56:57], v[58:59]
	v_pk_add_f32 v[54:55], v[54:55], v[62:63]
	v_pk_add_f32 v[58:59], v[52:53], v[60:61]
	v_pk_add_f32 v[60:61], v[50:51], v[64:65]
	v_cvt_pk_bf16_f32 v50, v54, v55
	v_cvt_pk_bf16_f32 v51, v56, v57
	v_cvt_pk_bf16_f32 v52, v60, v61
	v_cvt_pk_bf16_f32 v53, v58, v59
	flat_store_dwordx4 v[70:71], v[50:53] offset:256
	s_nop 1
	v_mul_f32_e32 v52, v55, v55
	v_mul_f32_e32 v53, v57, v57
	v_mul_f32_e32 v51, v61, v61
	v_fmac_f32_e32 v52, v54, v54
	v_fmac_f32_e32 v53, v56, v56
	v_mul_f32_e32 v50, v59, v59
	v_fmac_f32_e32 v51, v60, v60
	v_add_f32_e32 v52, v52, v53
	v_fmac_f32_e32 v50, v58, v58
	v_add_f32_e32 v51, v51, v52
	v_add_f32_e32 v50, v50, v51
	v_add_f32_e32 v50, v66, v50
	ds_bpermute_b32 v51, v149, v50
	s_waitcnt lgkmcnt(0)
	v_add_f32_e32 v50, v50, v51
	ds_bpermute_b32 v51, v150, v50
	s_and_saveexec_b64 s[22:23], s[40:41]
	s_cbranch_execz .LBB0_1165
	s_waitcnt lgkmcnt(0)
	v_add_f32_e32 v50, v50, v51
	ds_write_b32 v159, v50
; #define LAS __attribute__((address_space(3)))
; DI float shx(float v, int m, int lane) { return __builtin_bit_cast(float, __builtin_amdgcn_ds_bpermute((lane ^ m) << 2, __builtin_bit_cast(int, v))); }
; DI unsigned pk2(float lo, float hi) { f32x2_t v = {lo, hi}; bf16x2_t b = __builtin_convertvector(v, bf16x2_t); return __builtin_bit_cast(unsigned, b); }
;     DI void operator()(const f32x4 (&acc)[2][2][4][2], const pg8::Unit& u, int wr, int wc, int fr, int fq) const {
;     ...
;             for (int m = 0; m < 4; ++m) {
;                 const int row = u.pm * 256 + ai * 128 + wr * 64 + m * 16 + fr;
;                 float sq = 0.f;
; #pragma unroll
;                 for (int bj = 0; bj < 2; ++bj) {
;                     const size_t off = (size_t)row * DM + u.pn * 256 + bj * 128 + wc * 32 + 8 * fq;
;                     const u32x4 r = *(const u32x4*)(xb + off);
;                     f32x4 a, b;
;                     a[0] = __builtin_bit_cast(float, r.x << 16); a[1] = __builtin_bit_cast(float, r.x & 0xffff0000u); a[2] = __builtin_bit_cast(float, r.y << 16); a[3] = __builtin_bit_cast(float, r.y & 0xffff0000u);
;                     b[0] = __builtin_bit_cast(float, r.z << 16); b[1] = __builtin_bit_cast(float, r.z & 0xffff0000u); b[2] = __builtin_bit_cast(float, r.w << 16); b[3] = __builtin_bit_cast(float, r.w & 0xffff0000u);
;                     a += acc[ai][bj][m][0]; b += acc[ai][bj][m][1];
;                     if (xout) { *(f32x4*)(xout + off) = a; *(f32x4*)(xout + off + 4) = b; }
;                     else { u32x4 w; w.x = pk2(a[0], a[1]); w.y = pk2(a[2], a[3]); w.z = pk2(b[0], b[1]); w.w = pk2(b[2], b[3]); *(u32x4*)(xb + off) = w; }
;                     sq += (a[0] * a[0] + a[1] * a[1]) + (a[2] * a[2] + a[3] * a[3]) + (b[0] * b[0] + b[1] * b[1]) + (b[2] * b[2] + b[3] * b[3]);
;                 }
;                 if (ssout) { const int lane_ = fq * 16 + fr; sq += shx(sq, 16, lane_); sq += shx(sq, 32, lane_);
;                     if (fq == 0) *(LAS float*)(red + ((ai * 128 + wr * 64 + m * 16 + fr) * 4 + wc) * 4) = sq; }
.LBB0_1165:
	s_or_b64 exec, exec, s[22:23]
	v_add_u32_e32 v50, 0x90, v146
	s_waitcnt lgkmcnt(0)
	v_ashrrev_i32_e32 v51, 31, v50
	v_lshlrev_b64 v[50:51], 12, v[50:51]
	v_lshl_add_u64 v[50:51], s[28:29], 0, v[50:51]
	v_lshl_add_u64 v[50:51], s[20:21], 1, v[50:51]
	v_lshl_add_u64 v[54:55], v[50:51], 0, v[0:1]
	v_lshlrev_b32_e32 v56, 16, v220
	v_and_b32_e32 v57, 0xffff0000, v220
	v_lshlrev_b32_e32 v50, 16, v221
	v_and_b32_e32 v51, 0xffff0000, v221
	v_lshlrev_b32_e32 v58, 16, v222
	v_and_b32_e32 v59, 0xffff0000, v222
	v_lshlrev_b32_e32 v52, 16, v223
	v_and_b32_e32 v53, 0xffff0000, v223
	v_pk_add_f32 v[48:49], v[48:49], v[50:51]
	v_pk_add_f32 v[46:47], v[46:47], v[56:57]
	v_pk_add_f32 v[50:51], v[44:45], v[52:53]
	v_pk_add_f32 v[52:53], v[42:43], v[58:59]
	v_cvt_pk_bf16_f32 v42, v46, v47
	v_cvt_pk_bf16_f32 v43, v48, v49
	v_cvt_pk_bf16_f32 v44, v52, v53
	v_cvt_pk_bf16_f32 v45, v50, v51
	flat_store_dwordx4 v[54:55], v[42:45]
	s_nop 1
	v_mul_f32_e32 v42, v47, v47
	v_mul_f32_e32 v43, v49, v49
	v_fmac_f32_e32 v42, v46, v46
	v_fmac_f32_e32 v43, v48, v48
	v_add_f32_e32 v42, v42, v43
	v_mul_f32_e32 v43, v53, v53
	v_fmac_f32_e32 v43, v52, v52
	v_add_f32_e32 v42, v43, v42
	v_mul_f32_e32 v43, v51, v51
	v_fmac_f32_e32 v43, v50, v50
	v_add_f32_e32 v50, v43, v42
	v_lshlrev_b32_e32 v46, 16, v224
	v_and_b32_e32 v47, 0xffff0000, v224
	v_lshlrev_b32_e32 v42, 16, v225
	v_and_b32_e32 v43, 0xffff0000, v225
	v_lshlrev_b32_e32 v48, 16, v226
	v_and_b32_e32 v49, 0xffff0000, v226
	v_lshlrev_b32_e32 v44, 16, v227
	v_and_b32_e32 v45, 0xffff0000, v227
	v_pk_add_f32 v[40:41], v[40:41], v[42:43]
	v_pk_add_f32 v[38:39], v[38:39], v[46:47]
	v_pk_add_f32 v[42:43], v[36:37], v[44:45]
	v_pk_add_f32 v[44:45], v[34:35], v[48:49]
	v_cvt_pk_bf16_f32 v34, v38, v39
	v_cvt_pk_bf16_f32 v35, v40, v41
	v_cvt_pk_bf16_f32 v36, v44, v45
	v_cvt_pk_bf16_f32 v37, v42, v43
	flat_store_dwordx4 v[54:55], v[34:37] offset:256
	s_nop 1
	v_mul_f32_e32 v36, v39, v39
	v_mul_f32_e32 v37, v41, v41
	v_mul_f32_e32 v35, v45, v45
	v_fmac_f32_e32 v36, v38, v38
	v_fmac_f32_e32 v37, v40, v40
	v_mul_f32_e32 v34, v43, v43
	v_fmac_f32_e32 v35, v44, v44
	v_add_f32_e32 v36, v36, v37
	v_fmac_f32_e32 v34, v42, v42
	v_add_f32_e32 v35, v35, v36
	v_add_f32_e32 v34, v34, v35
	v_add_f32_e32 v34, v50, v34
	ds_bpermute_b32 v35, v149, v34
	s_waitcnt lgkmcnt(0)
	v_add_f32_e32 v34, v34, v35
	ds_bpermute_b32 v35, v150, v34
	s_and_saveexec_b64 s[22:23], s[40:41]
	s_cbranch_execz .LBB0_1167
	s_waitcnt lgkmcnt(0)
	v_add_f32_e32 v34, v34, v35
	ds_write_b32 v161, v34 offset:2304
; #define LAS __attribute__((address_space(3)))
; DI float shx(float v, int m, int lane) { return __builtin_bit_cast(float, __builtin_amdgcn_ds_bpermute((lane ^ m) << 2, __builtin_bit_cast(int, v))); }
; DI unsigned pk2(float lo, float hi) { f32x2_t v = {lo, hi}; bf16x2_t b = __builtin_convertvector(v, bf16x2_t); return __builtin_bit_cast(unsigned, b); }
;     DI void operator()(const f32x4 (&acc)[2][2][4][2], const pg8::Unit& u, int wr, int wc, int fr, int fq) const {
;     ...
;             for (int m = 0; m < 4; ++m) {
;                 const int row = u.pm * 256 + ai * 128 + wr * 64 + m * 16 + fr;
;                 float sq = 0.f;
; #pragma unroll
;                 for (int bj = 0; bj < 2; ++bj) {
;                     const size_t off = (size_t)row * DM + u.pn * 256 + bj * 128 + wc * 32 + 8 * fq;
;                     const u32x4 r = *(const u32x4*)(xb + off);
;                     f32x4 a, b;
;                     a[0] = __builtin_bit_cast(float, r.x << 16); a[1] = __builtin_bit_cast(float, r.x & 0xffff0000u); a[2] = __builtin_bit_cast(float, r.y << 16); a[3] = __builtin_bit_cast(float, r.y & 0xffff0000u);
;                     b[0] = __builtin_bit_cast(float, r.z << 16); b[1] = __builtin_bit_cast(float, r.z & 0xffff0000u); b[2] = __builtin_bit_cast(float, r.w << 16); b[3] = __builtin_bit_cast(float, r.w & 0xffff0000u);
;                     a += acc[ai][bj][m][0]; b += acc[ai][bj][m][1];
;                     if (xout) { *(f32x4*)(xout + off) = a; *(f32x4*)(xout + off + 4) = b; }
;                     else { u32x4 w; w.x = pk2(a[0], a[1]); w.y = pk2(a[2], a[3]); w.z = pk2(b[0], b[1]); w.w = pk2(b[2], b[3]); *(u32x4*)(xb + off) = w; }
;                     sq += (a[0] * a[0] + a[1] * a[1]) + (a[2] * a[2] + a[3] * a[3]) + (b[0] * b[0] + b[1] * b[1]) + (b[2] * b[2] + b[3] * b[3]);
;                 }
;                 if (ssout) { const int lane_ = fq * 16 + fr; sq += shx(sq, 16, lane_); sq += shx(sq, 32, lane_);
;                     if (fq == 0) *(LAS float*)(red + ((ai * 128 + wr * 64 + m * 16 + fr) * 4 + wc) * 4) = sq; }
.LBB0_1167:
	s_or_b64 exec, exec, s[22:23]
	v_add_u32_e32 v34, 0xa0, v146
	s_waitcnt lgkmcnt(0)
	v_ashrrev_i32_e32 v35, 31, v34
	v_lshlrev_b64 v[34:35], 12, v[34:35]
	v_lshl_add_u64 v[34:35], s[28:29], 0, v[34:35]
	v_lshl_add_u64 v[34:35], s[20:21], 1, v[34:35]
	v_lshl_add_u64 v[38:39], v[34:35], 0, v[0:1]
	v_lshlrev_b32_e32 v40, 16, v236
	v_and_b32_e32 v41, 0xffff0000, v236
	v_lshlrev_b32_e32 v34, 16, v237
	v_and_b32_e32 v35, 0xffff0000, v237
	v_lshlrev_b32_e32 v42, 16, v238
	v_and_b32_e32 v43, 0xffff0000, v238
	v_lshlrev_b32_e32 v36, 16, v239
	v_and_b32_e32 v37, 0xffff0000, v239
	v_pk_add_f32 v[32:33], v[32:33], v[34:35]
	v_pk_add_f32 v[30:31], v[30:31], v[40:41]
	v_pk_add_f32 v[34:35], v[28:29], v[36:37]
	v_pk_add_f32 v[36:37], v[26:27], v[42:43]
	v_cvt_pk_bf16_f32 v26, v30, v31
	v_cvt_pk_bf16_f32 v27, v32, v33
	v_cvt_pk_bf16_f32 v28, v36, v37
	v_cvt_pk_bf16_f32 v29, v34, v35
	flat_store_dwordx4 v[38:39], v[26:29]
	s_nop 1
	v_mul_f32_e32 v26, v31, v31
	v_mul_f32_e32 v27, v33, v33
	v_fmac_f32_e32 v26, v30, v30
	v_fmac_f32_e32 v27, v32, v32
	v_add_f32_e32 v26, v26, v27
	v_mul_f32_e32 v27, v37, v37
	v_fmac_f32_e32 v27, v36, v36
	v_add_f32_e32 v26, v27, v26
	v_mul_f32_e32 v27, v35, v35
	v_fmac_f32_e32 v27, v34, v34
	v_add_f32_e32 v34, v27, v26
	v_lshlrev_b32_e32 v30, 16, v240
	v_and_b32_e32 v31, 0xffff0000, v240
	v_lshlrev_b32_e32 v26, 16, v241
	v_and_b32_e32 v27, 0xffff0000, v241
	v_lshlrev_b32_e32 v32, 16, v242
	v_and_b32_e32 v33, 0xffff0000, v242
	v_lshlrev_b32_e32 v28, 16, v243
	v_and_b32_e32 v29, 0xffff0000, v243
	v_pk_add_f32 v[24:25], v[24:25], v[26:27]
	v_pk_add_f32 v[22:23], v[22:23], v[30:31]
	v_pk_add_f32 v[26:27], v[20:21], v[28:29]
	v_pk_add_f32 v[28:29], v[18:19], v[32:33]
	v_cvt_pk_bf16_f32 v18, v22, v23
	v_cvt_pk_bf16_f32 v19, v24, v25
	v_cvt_pk_bf16_f32 v20, v28, v29
	v_cvt_pk_bf16_f32 v21, v26, v27
	flat_store_dwordx4 v[38:39], v[18:21] offset:256
	s_nop 1
	v_mul_f32_e32 v20, v23, v23
	v_mul_f32_e32 v21, v25, v25
	v_mul_f32_e32 v19, v29, v29
	v_fmac_f32_e32 v20, v22, v22
	v_fmac_f32_e32 v21, v24, v24
	v_mul_f32_e32 v18, v27, v27
	v_fmac_f32_e32 v19, v28, v28
	v_add_f32_e32 v20, v20, v21
	v_fmac_f32_e32 v18, v26, v26
	v_add_f32_e32 v19, v19, v20
	v_add_f32_e32 v18, v18, v19
	v_add_f32_e32 v18, v34, v18
	ds_bpermute_b32 v19, v149, v18
	s_waitcnt lgkmcnt(0)
	v_add_f32_e32 v18, v18, v19
	ds_bpermute_b32 v19, v150, v18
	s_and_saveexec_b64 s[22:23], s[40:41]
	s_cbranch_execz .LBB0_1169
	s_waitcnt lgkmcnt(0)
	v_add_f32_e32 v18, v18, v19
	ds_write_b32 v161, v18 offset:2560
.LBB0_1169:
	s_or_b64 exec, exec, s[22:23]
	v_add_u32_e32 v18, 0xb0, v146
	s_waitcnt lgkmcnt(0)
	v_ashrrev_i32_e32 v19, 31, v18
	v_lshlrev_b64 v[18:19], 12, v[18:19]
	v_lshl_add_u64 v[18:19], s[28:29], 0, v[18:19]
	v_lshl_add_u64 v[18:19], s[20:21], 1, v[18:19]
	v_lshl_add_u64 v[22:23], v[18:19], 0, v[0:1]
	v_lshlrev_b32_e32 v24, 16, v244
	v_and_b32_e32 v25, 0xffff0000, v244
	v_lshlrev_b32_e32 v18, 16, v245
	v_and_b32_e32 v19, 0xffff0000, v245
	v_lshlrev_b32_e32 v26, 16, v246
	v_and_b32_e32 v27, 0xffff0000, v246
	v_lshlrev_b32_e32 v20, 16, v247
	v_and_b32_e32 v21, 0xffff0000, v247
	v_pk_add_f32 v[16:17], v[16:17], v[18:19]
	v_pk_add_f32 v[14:15], v[14:15], v[24:25]
	v_pk_add_f32 v[18:19], v[12:13], v[20:21]
	v_pk_add_f32 v[20:21], v[10:11], v[26:27]
	v_cvt_pk_bf16_f32 v10, v14, v15
	v_cvt_pk_bf16_f32 v11, v16, v17
	v_cvt_pk_bf16_f32 v12, v20, v21
	v_cvt_pk_bf16_f32 v13, v18, v19
	flat_store_dwordx4 v[22:23], v[10:13]
	v_mul_f32_e32 v0, v15, v15
	v_fmac_f32_e32 v0, v14, v14
	v_mul_f32_e32 v10, v17, v17
	v_fmac_f32_e32 v10, v16, v16
	v_add_f32_e32 v0, v0, v10
	v_mul_f32_e32 v10, v21, v21
	v_fmac_f32_e32 v10, v20, v20
	v_add_f32_e32 v0, v10, v0
	v_mul_f32_e32 v10, v19, v19
	v_fmac_f32_e32 v10, v18, v18
	v_add_f32_e32 v0, v10, v0
	v_lshlrev_b32_e32 v14, 16, v248
	v_and_b32_e32 v15, 0xffff0000, v248
	v_lshlrev_b32_e32 v10, 16, v249
	v_and_b32_e32 v11, 0xffff0000, v249
	v_lshlrev_b32_e32 v16, 16, v250
	v_and_b32_e32 v17, 0xffff0000, v250
	v_lshlrev_b32_e32 v12, 16, v251
	v_and_b32_e32 v13, 0xffff0000, v251
	v_pk_add_f32 v[8:9], v[8:9], v[10:11]
	v_pk_add_f32 v[6:7], v[6:7], v[14:15]
	v_pk_add_f32 v[10:11], v[4:5], v[12:13]
	v_pk_add_f32 v[12:13], v[2:3], v[16:17]
	v_cvt_pk_bf16_f32 v2, v6, v7
	v_cvt_pk_bf16_f32 v3, v8, v9
	v_cvt_pk_bf16_f32 v4, v12, v13
	v_cvt_pk_bf16_f32 v5, v10, v11
	flat_store_dwordx4 v[22:23], v[2:5] offset:256
	s_nop 1
	v_mul_f32_e32 v4, v7, v7
	v_mul_f32_e32 v5, v9, v9
	v_mul_f32_e32 v3, v13, v13
	v_fmac_f32_e32 v4, v6, v6
	v_fmac_f32_e32 v5, v8, v8
	v_mul_f32_e32 v2, v11, v11
	v_fmac_f32_e32 v3, v12, v12
	v_add_f32_e32 v4, v4, v5
	v_fmac_f32_e32 v2, v10, v10
	v_add_f32_e32 v3, v3, v4
	v_add_f32_e32 v2, v2, v3
	v_add_f32_e32 v0, v0, v2
	ds_bpermute_b32 v2, v149, v0
	s_waitcnt lgkmcnt(0)
	v_add_f32_e32 v0, v0, v2
	ds_bpermute_b32 v2, v150, v0
	s_and_saveexec_b64 s[20:21], s[40:41]
	s_cbranch_execz .LBB0_1171
	s_waitcnt lgkmcnt(0)
	v_add_f32_e32 v0, v0, v2
	ds_write_b32 v161, v0 offset:2816
